# scan: BT/KT fragments via ds_read_b64_tr_b16 of BK, drop 16 ds_write_b16 per wave per superchunk
# speedup vs baseline: 1.0035x; 1.0035x over previous
.LBB0_500:
	v_writelane_b32 v255, s80, 6
	v_writelane_b32 v255, s78, 4
	s_nop 1
	v_writelane_b32 v255, s79, 5
	v_writelane_b32 v255, s72, 7
	v_writelane_b32 v255, s97, 8
	s_or_b64 exec, exec, s[4:5]
	s_mov_b64 s[6:7], s[76:77]
	v_writelane_b32 v255, s71, 9
	s_cmpk_gt_i32 s71, 0xff
	s_barrier
	s_cbranch_scc1 .LBB0_614
	s_bfe_u32 s0, s70, 0x20006
	s_lshl_b32 s69, s0, 6
	s_cmpk_gt_u32 s70, 0xff
	v_or_b32_e32 v2, s69, v252
	s_cselect_b64 s[4:5], -1, 0
	v_lshlrev_b32_e32 v2, 7, v2
	s_or_b32 s73, s69, 0x100
	v_and_b32_e32 v141, 0x7c00, v2
	v_or_b32_e32 v2, s73, v252
	v_lshlrev_b32_e32 v2, 7, v2
	s_or_b32 s74, s69, 0x200
	v_and_b32_e32 v142, 0xfc00, v2
	v_or_b32_e32 v2, s74, v252
	s_movk_i32 s1, 0x20f
	v_mov_b32_e32 v3, 0xfffffdf0
	v_cmp_lt_u32_e32 vcc, s1, v2
	v_bfrev_b32_e32 v4, 64
	s_or_b32 s75, s69, 0x300
	v_cndmask_b32_e32 v3, 0, v3, vcc
	v_add_lshl_u32 v2, v3, v2, 7
	v_cndmask_b32_e32 v4, 0, v4, vcc
	v_and_b32_e32 v2, 0xfffffc00, v2
	v_add_u32_e32 v143, v2, v4
	v_or_b32_e32 v2, s75, v252
	v_mov_b32_e32 v3, 0x7ffef800
	v_lshl_add_u32 v2, v2, 7, v3
	v_and_b32_e32 v2, 0xfc00, v2
	s_or_b32 s76, s69, 0x400
	v_or_b32_e32 v144, 0x2000000, v2
	v_or_b32_e32 v2, s76, v252
	v_mul_u32_u24_e32 v3, 0x3e1, v2
	v_lshrrev_b32_e32 v3, 19, v3
	v_mul_i32_i24_e32 v4, 0xfffffdf0, v3
	v_add_lshl_u32 v2, v4, v2, 7
	v_and_b32_e32 v2, 0xfffffc00, v2
	s_or_b32 s77, s69, 0x500
	v_lshl_add_u32 v145, v3, 25, v2
	v_or_b32_e32 v2, s77, v252
	v_mov_b32_e32 v3, 0x7ffdf000
	v_lshl_add_u32 v2, v2, 7, v3
	v_and_b32_e32 v2, 0xfc00, v2
	s_or_b32 s78, s69, 0x600
	v_or_b32_e32 v146, 0x4000000, v2
	v_or_b32_e32 v2, s78, v252
	s_movk_i32 s79, 0x630
	v_cmp_gt_u32_e32 vcc, s79, v2
	s_and_b64 s[8:9], s[4:5], vcc
	v_writelane_b32 v255, s8, 2
	v_and_b32_e32 v6, 48, v252
	v_and_b32_e32 v3, 15, v0
	v_writelane_b32 v255, s9, 3
	v_lshrrev_b32_e32 v4, 4, v252
	v_readlane_b32 s17, v255, 7
	s_cmp_eq_u32 s17, 7
	s_cselect_b64 s[8:9], -1, 0
	s_lshr_b32 s1, s70, 7
	s_lshl_b32 s80, s1, 4
	s_add_i32 s2, s69, 0xf0
	s_lshl_b32 s1, s1, 6
	v_writelane_b32 v255, s2, 10
	s_add_i32 s2, s1, 0
	v_add_u32_e32 v148, s2, v6
	s_lshl_b32 s2, s17, 5
	s_and_b32 s16, s2, 32
	v_lshl_or_b32 v5, v4, 2, s80
	v_lshrrev_b32_e32 v8, 2, v0
	s_lshl_b32 s82, s0, 4
	v_or_b32_e32 v150, s16, v3
	s_movk_i32 s0, 0x44
	v_or_b32_e32 v7, s1, v3
	v_bitop3_b32 v8, v4, v8, 3 bitop3:0x78
	s_add_i32 s1, 0, 0x1a540
	v_mul_lo_u32 v9, v5, s0
	v_or_b32_e32 v12, 16, v150
	v_lshl_add_u32 v149, v8, 4, s1
	v_bitop3_b32 v8, v4, v0, 7 bitop3:0x78
	v_add_u32_e32 v10, v9, v150
	v_bitop3_b32 v1, v4, v1, 4 bitop3:0x36
	v_add_u32_e32 v9, v9, v12
	v_lshlrev_b32_e32 v6, 1, v3
	v_cmp_eq_u32_e64 s[14:15], 3, v4
	v_lshlrev_b32_e32 v8, 4, v8
	v_lshl_add_u32 v151, v10, 2, 0
	v_lshlrev_b32_e32 v10, 7, v150
	v_lshlrev_b32_e32 v1, 4, v1
	v_lshl_add_u32 v153, v9, 2, 0
	v_lshlrev_b32_e32 v9, 7, v12
	v_lshlrev_b32_e32 v4, 5, v4
	v_or_b32_e32 v11, v10, v8
	v_or_b32_e32 v10, v10, v1
	v_or_b32_e32 v8, v9, v8
	v_or_b32_e32 v1, v9, v1
	v_lshlrev_b32_e32 v9, 6, v5
	v_bitop3_b32 v4, s16, v4, v6 bitop3:0x36
	v_and_or_b32 v4, v4, 56, v9
	v_or_b32_e32 v9, v4, v191
	v_lshlrev_b32_e32 v9, 1, v9
	s_add_i32 s89, 0, 0x12540
	s_add_i32 s90, 0, 0x16540
	s_add_i32 s91, 0, 0x18540
	s_add_i32 s92, 0, 0x14540
	v_add_u32_e32 v154, s89, v9
	v_add_u32_e32 v155, s90, v9
	v_add_u32_e32 v156, s91, v9
	v_add_u32_e32 v157, s92, v9
	v_or_b32_e32 v9, 1, v5
	v_lshlrev_b32_e32 v12, 6, v9
	v_lshlrev_b32_e32 v9, 3, v9
	v_bitop3_b32 v9, v9, s16, v6 bitop3:0x1e
	v_and_or_b32 v9, v9, 56, v12
	v_or_b32_e32 v12, v9, v191
	v_lshlrev_b32_e32 v12, 1, v12
	v_add_u32_e32 v158, s89, v12
	v_add_u32_e32 v159, s90, v12
	v_add_u32_e32 v160, s91, v12
	v_add_u32_e32 v161, s92, v12
	v_or_b32_e32 v12, 2, v5
	v_lshlrev_b32_e32 v13, 6, v12
	v_lshlrev_b32_e32 v12, 3, v12
	v_bitop3_b32 v12, v12, s16, v6 bitop3:0x1e
	v_and_or_b32 v12, v12, 56, v13
	v_or_b32_e32 v13, v12, v191
	v_lshlrev_b32_e32 v13, 1, v13
	v_or_b32_e32 v5, 3, v5
	v_add_u32_e32 v162, s89, v13
	v_add_u32_e32 v163, s90, v13
	v_add_u32_e32 v164, s91, v13
	v_add_u32_e32 v165, s92, v13
	v_lshlrev_b32_e32 v13, 6, v5
	v_lshlrev_b32_e32 v5, 3, v5
	v_bitop3_b32 v5, v5, s16, v6 bitop3:0x1e
	v_and_or_b32 v5, v5, 56, v13
	v_or_b32_e32 v6, v5, v191
	v_lshlrev_b32_e32 v6, 1, v6
	v_add_u32_e32 v166, s89, v6
	v_add_u32_e32 v167, s90, v6
	v_add_u32_e32 v168, s91, v6
	v_add_u32_e32 v169, s92, v6
	v_or_b32_e32 v6, s16, v7
	v_lshlrev_b32_e32 v170, 6, v6
	v_lshl_add_u32 v171, v6, 2, 0
	v_or_b32_e32 v6, 4, v191
	v_or_b32_e32 v4, v4, v6
	s_lshl_b32 s84, s17, 4
	v_lshlrev_b32_e32 v4, 1, v4
	s_load_dwordx4 s[16:19], s[6:7], 0xa8
	v_add_u32_e32 v172, s89, v4
	v_add_u32_e32 v173, s90, v4
	v_add_u32_e32 v174, s91, v4
	v_add_u32_e32 v175, s92, v4
	v_or_b32_e32 v4, v9, v6
	v_lshlrev_b32_e32 v4, 1, v4
	s_add_i32 s88, s2, 0
	v_add_u32_e32 v176, s89, v4
	v_add_u32_e32 v177, s90, v4
	v_add_u32_e32 v178, s91, v4
	v_add_u32_e32 v179, s92, v4
	v_or_b32_e32 v4, v12, v6
	s_add_i32 s83, s69, 0
	s_add_i32 s85, s88, 0x20540
	s_add_i32 s86, s88, 0x20d40
	s_add_i32 s87, s88, 0x21540
	s_add_i32 s88, s88, 0x21d40
	v_lshlrev_b32_e32 v4, 1, v4
	v_add_u32_e32 v180, s89, v4
	v_add_u32_e32 v181, s90, v4
	v_add_u32_e32 v182, s91, v4
	v_add_u32_e32 v183, s92, v4
	v_or_b32_e32 v4, v5, v6
	s_waitcnt lgkmcnt(0)
	s_add_u32 s93, s16, 0x20000
	v_mov_b32_e32 v5, 0x1f000
	v_add_u32_e32 v193, 0, v1
	v_mbcnt_lo_u32_b32 v1, -1, 0
	v_lshlrev_b32_e32 v4, 1, v4
	s_addc_u32 s94, s17, 0
	v_lshl_add_u32 v2, v2, 7, v5
	s_add_i32 s0, 0, 0x4000
	v_mbcnt_hi_u32_b32 v1, -1, v1
	v_add_u32_e32 v184, s89, v4
	v_add_u32_e32 v185, s90, v4
	v_add_u32_e32 v186, s91, v4
	v_add_u32_e32 v187, s92, v4
	v_or_b32_e32 v4, 0x400, v170
	v_and_b32_e32 v2, 0x1fc00, v2
	v_writelane_b32 v255, s0, 11
	s_mov_b32 s55, 0x20000
	v_and_or_b32 v1, v1, 64, v3
	v_and_b32_e32 v140, 0x70, v195
	s_mov_b32 s67, 0
	v_xor_b32_e32 v147, 0x1f8, v190
	v_cmp_gt_u32_e64 s[10:11], 16, v252
	v_cmp_lt_u32_e64 s[12:13], 31, v252
	v_lshl_add_u32 v152, v150, 2, 0
	v_or_b32_e32 v188, 0x4000000, v2
	s_mov_b32 s68, 0xbfb8aa3b
	s_mov_b32 s96, 0x2aaaaaab
	s_movk_i32 s97, 0xc0
	s_movk_i32 s64, 0x680
	s_mov_b32 s54, 0x4200400
	s_mov_b32 s26, 0x10000
	s_mov_b32 s58, 0x10000
	s_mov_b32 s59, s55
	v_mov_b32_e32 v5, 0
	s_movk_i32 s65, 0x208
	s_movk_i32 s34, 0x41f
	s_mov_b32 s62, 0x7ffffff0
	s_mov_b32 s63, s55
	s_mov_b32 s35, 0x10540
	v_add_u32_e32 v189, 0, v11
	v_add_u32_e32 v191, 0, v10
	v_add_u32_e32 v192, 0, v8
	s_mov_b32 s70, 0xbf60028a
	v_add_u32_e32 v194, v149, v4
	v_mov_b32_e32 v195, 0x3a27c5ac
	v_mov_b32_e32 v196, 1
	s_add_i32 s72, 0, 0x1ed40
	s_add_i32 s71, 0, 0x1f540
	s_add_i32 s33, 0, 0x1e540
	v_bfrev_b32_e32 v197, -2
	v_mov_b32_e32 v198, 0x9e20
	v_mov_b32_e32 v199, 0x5800
	v_mov_b32_e32 v200, 0x12800000
	v_mov_b32_e32 v201, 0x10800000
	v_lshlrev_b32_e32 v202, 2, v1
	v_lshrrev_b32_e32 v241, 2, v252
	v_lshrrev_b32_e32 v242, 4, v252
	v_and_b32_e32 v243, 3, v252
	v_xor_b32_e32 v242, v242, v243
	v_lshlrev_b32_e32 v242, 4, v242
	v_lshl_add_u32 v241, v241, 6, v242
	v_lshl_add_u32 v241, s82, 8, v241
	v_add_u32_e32 v241, 0x1a540, v241
	v_readlane_b32 s95, v255, 9
	s_branch .LBB0_503

.LBB0_552:
	s_lshl_b32 s30, s51, 6
	s_sub_i32 s22, 0x800, s30
	s_sub_i32 s2, s30, 64
	s_and_b64 s[18:19], s[16:17], exec
	v_mov_b32_e32 v2, v0
	s_cselect_b32 s18, s22, s2
	s_or_b32 s18, s18, 63
	v_ashrrev_i32_e32 v3, 3, v2
	v_sub_u32_e32 v4, s18, v3
	v_add_u32_e32 v3, s2, v3
	v_cndmask_b32_e64 v3, v3, v4, s[16:17]
	v_lshlrev_b32_e32 v2, 3, v2
	v_add_u32_e32 v4, s50, v3
	v_and_b32_e32 v2, 56, v2
	v_lshlrev_b32_e32 v66, 9, v4
	s_cmp_gt_u32 s51, 16
	v_or3_b32 v66, v66, s1, v2
	v_add_lshl_u32 v3, v3, s66, 9
	v_lshl_add_u32 v66, v66, 1, v200
	s_cselect_b64 vcc, -1, 0
	v_or3_b32 v2, v3, s1, v2
	v_cndmask_b32_e32 v66, v197, v66, vcc
	v_lshl_add_u32 v2, v2, 1, v201
	v_lshl_add_u32 v3, v4, 5, s27
	v_mov_b32_e32 v90, v0
	v_cndmask_b32_e32 v2, v197, v2, vcc
	v_cndmask_b32_e32 v3, v197, v3, vcc
	buffer_load_dwordx4 v[70:73], v66, s[60:63], 0 offen sc1
	s_nop 0
	buffer_load_dwordx4 v[66:69], v2, s[60:63], 0 offen
	buffer_load_dword v213, v3, s[60:63], 0 offen sc1
	s_bitcmp0_b32 s51, 0
	v_and_b32_e32 v91, 63, v90
	v_ashrrev_i32_e32 v92, 6, v90
	v_lshlrev_b32_e32 v2, 10, v92
	v_lshlrev_b32_e32 v3, 1, v91
	v_add3_u32 v3, 0, v2, v3
	v_lshlrev_b32_e32 v2, 2, v91
	v_add_u32_e32 v4, s0, v2
	v_add_u32_e32 v74, 0, v2
	v_add_u32_e32 v75, s28, v2
	ds_read_b32 v2, v4 offset:17920
	ds_read_b32 v4, v74 offset:18176
	ds_read_b32 v74, v75 offset:17920
	ds_read_u16 v75, v3 offset:58688
	ds_read_u16 v79, v3 offset:59072
	ds_read_u16 v86, v3 offset:59200
	ds_read_u16 v87, v3 offset:59328
	ds_read_u16 v77, v3 offset:58944
	ds_read_u16 v80, v3 offset:58816
	ds_read_u16 v82, v3 offset:58432
	ds_read_u16 v83, v3 offset:58560
	s_waitcnt lgkmcnt(7)
	v_lshlrev_b32_e32 v76, 16, v75
	ds_read_u16 v75, v3 offset:59456
	ds_read_u16 v3, v3 offset:59584
	s_waitcnt lgkmcnt(5)
	v_lshlrev_b32_e32 v78, 16, v77
	s_waitcnt lgkmcnt(4)
	v_lshlrev_b32_e32 v77, 16, v80
	s_waitcnt lgkmcnt(2)
	v_lshlrev_b32_e32 v83, 16, v83
	v_lshlrev_b32_e32 v82, 16, v82
	v_pk_mov_b32 v[84:85], v[82:83], v[76:77] op_sel:[1,0]
	v_mov_b32_e32 v80, v77
	v_mov_b32_e32 v81, v78
	v_pk_mul_f32 v[84:85], v[4:5], v[84:85] op_sel_hi:[0,1]
	s_waitcnt lgkmcnt(0)
	v_pk_fma_f32 v[82:83], v[2:3], v[82:83], v[84:85] op_sel_hi:[0,1,1]
	v_pk_mul_f32 v[80:81], v[4:5], v[80:81] op_sel_hi:[0,1]
	v_lshlrev_b32_e32 v79, 16, v79
	v_pk_fma_f32 v[82:83], v[74:75], v[76:77], v[82:83] op_sel_hi:[0,1,1]
	v_pk_fma_f32 v[76:77], v[2:3], v[76:77], v[80:81] op_sel_hi:[0,1,1]
	v_lshlrev_b32_e32 v80, 16, v86
	v_lshlrev_b32_e32 v81, 16, v87
	v_lshlrev_b32_e32 v87, 16, v75
	v_mov_b32_e32 v86, v81
	v_pk_mov_b32 v[88:89], v[78:79], v[80:81] op_sel:[1,0]
	v_mov_b32_e32 v84, v87
	v_pk_mul_f32 v[88:89], v[4:5], v[88:89] op_sel_hi:[0,1]
	v_pk_mul_f32 v[86:87], v[4:5], v[86:87] op_sel_hi:[0,1]
	s_cselect_b32 s18, s35, 0x22540
	s_cmp_lg_u32 s51, 31
	v_pk_fma_f32 v[76:77], v[74:75], v[78:79], v[76:77] op_sel_hi:[0,1,1]
	v_lshlrev_b32_e32 v85, 16, v3
	v_pk_fma_f32 v[78:79], v[2:3], v[78:79], v[88:89] op_sel_hi:[0,1,1]
	v_pk_fma_f32 v[2:3], v[2:3], v[80:81], v[86:87] op_sel_hi:[0,1,1]
	s_cselect_b64 s[48:49], -1, 0
	s_add_i32 s31, s18, 0
	v_pk_fma_f32 v[78:79], v[74:75], v[80:81], v[78:79] op_sel_hi:[0,1,1]
	v_pk_fma_f32 v[2:3], v[74:75], v[84:85], v[2:3] op_sel_hi:[0,1,1]
	v_cvt_pk_bf16_f32 v75, v76, v77
	v_lshlrev_b32_e32 v77, 1, v92
	v_lshl_add_u32 v76, v91, 7, s31
	v_bitop3_b32 v80, v77, v90, 15 bitop3:0x78
	v_and_b32_e32 v4, 15, v90
	v_cvt_pk_bf16_f32 v74, v82, v83
	v_lshl_add_u32 v80, v80, 3, v76
	ds_write_b64 v80, v[74:75]
	v_cvt_pk_bf16_f32 v75, v2, v3
	v_bitop3_b32 v2, v77, v4, 1 bitop3:0x36
	v_cvt_pk_bf16_f32 v74, v78, v79
	v_lshl_add_u32 v2, v2, 3, v76
	ds_write_b64 v2, v[74:75]
	v_add_u32_e32 v2, 0x5800, v151
	ds_read2_b32 v[104:105], v2 offset1:16
	ds_read2_b32 v[118:119], v2 offset0:68 offset1:136
	v_add_u32_e32 v2, 0x9c00, v151
	ds_read2_b32 v[106:107], v2 offset0:136 offset1:152
	v_add_u32_e32 v2, 0x9e00, v151
	ds_read2_b32 v[120:121], v2 offset0:76 offset1:144
	v_add_u32_e32 v2, 0x5a00, v151
	ds_read2_b32 v[128:129], v2 offset0:76 offset1:144
	v_add_u32_e32 v2, 0xa000, v151
	v_add_u32_e32 v4, 0x4000, v152
	ds_read2_b32 v[126:127], v2 offset0:84 offset1:152
	ds_read_b128 v[74:77], v148 offset:20224
	ds_read_b32 v219, v151 offset:23888
	ds_read_b32 v3, v153 offset:41840
	ds_read_b32 v221, v151 offset:41840
	v_add_u32_e32 v2, 0x4000, v210
	ds_read2_b32 v[94:95], v4 offset0:64 offset1:80
	v_add_u32_e32 v4, 0x4000, v211
	ds_read2_b32 v[90:91], v2 offset1:16
	ds_read2_b32 v[92:93], v4 offset1:16
	ds_read2_b32 v[86:87], v2 offset0:192 offset1:208
	ds_read_b128 v[78:81], v189
	ds_read_b128 v[82:85], v189 offset:8192
	ds_read_b128 v[108:111], v191
	ds_read_b32 v99, v153 offset:23888
	s_waitcnt vmcnt(14) lgkmcnt(3)
	v_mfma_f32_16x16x32_bf16 v[78:81], v[10:13], v[78:81], 0
	v_add_u32_e32 v2, 0x4400, v152
	ds_read2_b32 v[102:103], v2 offset1:16
	ds_read2_b32 v[100:101], v4 offset0:192 offset1:208
	v_add_u32_e32 v2, 0x4800, v152
	s_waitcnt vmcnt(13) lgkmcnt(3)
	v_mfma_f32_16x16x32_bf16 v[136:139], v[6:9], v[108:111], v[78:81]
	ds_read2_b32 v[96:97], v2 offset0:128 offset1:144
	ds_read2_b32 v[88:89], v2 offset0:192 offset1:208
	s_nop 0
	ds_read_b128 v[78:81], v191 offset:8192
	v_add_u32_e32 v2, 0x4c00, v152
	ds_read2_b32 v[132:133], v2 offset0:64 offset1:80
	ds_read_b128 v[108:111], v192
	s_waitcnt vmcnt(12)
	v_mfma_f32_16x16x32_bf16 v[82:85], v[18:21], v[82:85], 0
	s_add_i32 s81, s30, 64
	s_sub_i32 s2, 0x780, s30
	s_cmp_eq_u32 s51, 31
	s_waitcnt vmcnt(11) lgkmcnt(2)
	v_mfma_f32_16x16x32_bf16 v[214:217], v[14:17], v[78:81], v[82:85]
	ds_read2_b32 v[116:117], v2 offset0:128 offset1:144
	ds_read_b128 v[78:81], v192 offset:8192
	s_nop 0
	ds_read_b128 v[82:85], v193
	v_add_u32_e32 v2, 0x5800, v153
	ds_read2_b32 v[112:113], v2 offset0:68 offset1:136
	s_waitcnt lgkmcnt(4)
	v_mfma_f32_16x16x32_bf16 v[10:13], v[10:13], v[108:111], 0
	v_add_u32_e32 v2, 0x9e00, v153
	ds_read2_b32 v[108:109], v2 offset0:76 offset1:144
	v_add_u32_e32 v2, 0x5a00, v153
	s_waitcnt lgkmcnt(2)
	v_mfma_f32_16x16x32_bf16 v[82:85], v[6:9], v[82:85], v[10:13]
	ds_read_b128 v[6:9], v193 offset:8192
	s_cselect_b32 s23, 0x7c0, s81
	ds_read2_b32 v[114:115], v2 offset0:76 offset1:144
	v_mfma_f32_16x16x32_bf16 v[10:13], v[18:21], v[78:81], 0
	v_add_u32_e32 v2, 0xa000, v153
	s_cselect_b32 s24, 31, s2
	s_and_b64 s[18:19], s[16:17], exec
	ds_read2_b32 v[110:111], v2 offset0:84 offset1:152
	v_mov_b32_e32 v2, v0
	s_cselect_b32 s18, s24, s23
	s_or_b32 s18, s18, 63
	v_and_or_b32 v4, v2, 15, s80
	s_waitcnt lgkmcnt(2)
	v_mfma_f32_16x16x32_bf16 v[78:81], v[14:17], v[6:9], v[10:13]
	v_sub_u32_e32 v6, s18, v4
	v_add_u32_e32 v4, s23, v4
	v_cndmask_b32_e64 v6, v4, v6, s[16:17]
	v_ashrrev_i32_e32 v7, 31, v6
	v_lshl_add_u64 v[6:7], v[6:7], 0, s[66:67]
	v_lshlrev_b64 v[6:7], 7, v[6:7]
	v_lshl_add_u64 v[8:9], s[36:37], 0, v[6:7]
	v_and_b32_e32 v4, 48, v2
	v_lshl_add_u64 v[6:7], s[38:39], 0, v[6:7]
	v_lshl_add_u64 v[14:15], v[6:7], 0, v[4:5]
	v_pk_add_f32 v[6:7], v[132:133], v[136:137] op_sel_hi:[0,1]
	v_exp_f32_e32 v6, v6
	v_exp_f32_e32 v7, v7
	v_pk_add_f32 v[10:11], v[132:133], v[138:139] op_sel_hi:[0,1]
	v_exp_f32_e32 v10, v10
	v_exp_f32_e32 v11, v11
	v_pk_add_f32 v[6:7], v[6:7], 1.0 op_sel_hi:[1,0]
	v_lshl_add_u64 v[8:9], v[8:9], 0, v[4:5]
	v_rcp_f32_e32 v16, v6
	v_rcp_f32_e32 v17, v7
	v_pk_add_f32 v[6:7], v[10:11], 1.0 op_sel_hi:[1,0]
	v_pk_add_f32 v[214:215], v[116:117], v[214:215] op_sel_hi:[0,1]
	v_rcp_f32_e32 v18, v6
	v_rcp_f32_e32 v19, v7
	v_pk_mul_f32 v[222:223], v[16:17], s[70:71] op_sel_hi:[1,0]
	global_load_dwordx4 v[10:13], v[8:9], off
	s_nop 0
	global_load_dwordx4 v[6:9], v[8:9], off offset:64
	v_pk_fma_f32 v[224:225], v[16:17], s[70:71], v[222:223] op_sel:[0,0,1] op_sel_hi:[1,0,0]
	v_mul_f32_e32 v2, 0xbf60028a, v19
	v_pk_fma_f32 v[226:227], v[18:19], s[70:71], v[224:225] op_sel_hi:[1,0,1]
	global_load_dwordx4 v[18:21], v[14:15], off
	s_nop 0
	global_load_dwordx4 v[14:17], v[14:15], off offset:64
	v_pk_add_f32 v[228:229], v[2:3], v[226:227] op_sel_hi:[0,1]
	ds_bpermute_b32 v136, v202, v228
	ds_bpermute_b32 v138, v202, v228 offset:64
	ds_bpermute_b32 v137, v202, v228 offset:128
	v_exp_f32_e32 v214, v214
	v_exp_f32_e32 v215, v215
	v_pk_add_f32 v[216:217], v[116:117], v[216:217] op_sel_hi:[0,1]
	v_exp_f32_e32 v216, v216
	v_exp_f32_e32 v217, v217
	s_waitcnt lgkmcnt(2)
	v_cndmask_b32_e64 v2, v136, 0, s[10:11]
	s_waitcnt lgkmcnt(1)
	v_cndmask_b32_e64 v4, 0, v138, s[12:13]
	v_pk_add_f32 v[214:215], v[214:215], 1.0 op_sel_hi:[1,0]
	v_add_f32_e32 v2, v2, v4
	s_waitcnt lgkmcnt(0)
	v_cndmask_b32_e64 v4, 0, v137, s[14:15]
	v_rcp_f32_e32 v214, v214
	v_rcp_f32_e32 v215, v215
	v_add_f32_e32 v2, v2, v4
	v_mov_b32_e32 v223, v224
	v_pk_add_f32 v[216:217], v[216:217], 1.0 op_sel_hi:[1,0]
	v_mov_b32_e32 v122, v106
	v_mov_b32_e32 v123, v120
	v_mov_b32_e32 v130, v121
	v_pk_add_f32 v[224:225], v[222:223], v[2:3] op_sel_hi:[1,0]
	v_mov_b32_e32 v227, v228
	v_rcp_f32_e32 v216, v216
	v_rcp_f32_e32 v217, v217
	v_pk_mul_f32 v[120:121], v[120:121], v[102:103] op_sel_hi:[1,0]
	v_mov_b32_e32 v131, v126
	ds_bpermute_b32 v139, v202, v228 offset:192
	v_pk_add_f32 v[226:227], v[226:227], v[2:3] op_sel_hi:[1,0]
	v_exp_f32_e32 v228, v224
	v_sub_f32_e32 v2, v224, v222
	v_pk_fma_f32 v[120:121], v[122:123], v[86:87], v[120:121] op_sel_hi:[1,0,1]
	v_pk_mul_f32 v[122:123], v[126:127], v[102:103] op_sel_hi:[1,0]
	v_exp_f32_e32 v222, v2
	v_pk_fma_f32 v[120:121], v[130:131], v[100:101], v[120:121] op_sel_hi:[1,0,1]
	v_pk_fma_f32 v[122:123], v[130:131], v[86:87], v[122:123] op_sel_hi:[1,0,1]
	v_pk_add_f32 v[130:131], v[214:215], -1.0 op_sel_hi:[1,0]
	v_exp_f32_e32 v229, v225
	v_exp_f32_e32 v230, v226
	v_exp_f32_e64 v232, -v224
	v_exp_f32_e64 v233, -v225
	v_pk_mul_f32 v[130:131], v[88:89], v[130:131] op_sel_hi:[0,1]
	v_mov_b32_e32 v220, v127
	v_pk_mul_f32 v[126:127], v[96:97], v[120:121] op_sel_hi:[0,1]
	v_pk_fma_f32 v[120:121], v[120:121], v[130:131], v[120:121]
	v_pk_add_f32 v[130:131], v[216:217], -1.0 op_sel_hi:[1,0]
	v_mov_b32_e32 v124, v104
	v_mov_b32_e32 v125, v118
	v_mov_b32_e32 v134, v119
	v_exp_f32_e32 v231, v227
	v_exp_f32_e64 v226, -v226
	v_exp_f32_e64 v227, -v227
	v_mov_b32_e32 v223, v228
	v_pk_mul_f32 v[118:119], v[118:119], v[94:95] op_sel_hi:[1,0]
	v_pk_fma_f32 v[122:123], v[220:221], v[100:101], v[122:123] op_sel_hi:[1,0,1]
	v_pk_mul_f32 v[126:127], v[74:75], v[126:127]
	v_pk_mul_f32 v[130:131], v[88:89], v[130:131] op_sel_hi:[0,1]
	v_mov_b32_e32 v135, v128
	v_mov_b32_e32 v218, v129
	v_pk_fma_f32 v[118:119], v[124:125], v[90:91], v[118:119] op_sel_hi:[1,0,1]
	v_pk_mul_f32 v[124:125], v[128:129], v[94:95] op_sel_hi:[1,0]
	v_pk_mul_f32 v[128:129], v[96:97], v[122:123] op_sel_hi:[0,1]
	v_pk_fma_f32 v[122:123], v[122:123], v[130:131], v[122:123]
	v_pk_mul_f32 v[130:131], v[126:127], v[222:223] neg_lo:[0,1] neg_hi:[0,1]
	v_pk_mul_f32 v[126:127], v[126:127], v[214:215]
	v_mov_b32_e32 v224, v229
	v_mov_b32_e32 v225, v230
	v_pk_fma_f32 v[118:119], v[134:135], v[92:93], v[118:119] op_sel_hi:[1,0,1]
	v_pk_mul_f32 v[128:129], v[76:77], v[128:129]
	v_pk_mul_f32 v[126:127], v[126:127], v[232:233]
	v_pk_fma_f32 v[124:125], v[134:135], v[90:91], v[124:125] op_sel_hi:[1,0,1]
	v_pk_mul_f32 v[134:135], v[128:129], v[224:225] neg_lo:[0,1] neg_hi:[0,1]
	v_pk_mul_f32 v[128:129], v[128:129], v[216:217]
	v_pk_mul_f32 v[120:121], v[120:121], v[232:233]
	v_pk_mul_f32 v[118:119], v[118:119], v[228:229]
	v_cvt_pk_bf16_f32 v2, v130, v126
	v_pk_fma_f32 v[124:125], v[218:219], v[92:93], v[124:125] op_sel_hi:[1,0,1]
	v_pk_mul_f32 v[128:129], v[128:129], v[226:227]
	v_cvt_pk_bf16_f32 v4, v120, v118
	ds_write_b16 v154, v2
	ds_write_b16_d16_hi v157, v4
	v_cvt_pk_bf16_f32 v2, v131, v127
	v_pk_mul_f32 v[122:123], v[122:123], v[226:227]
	v_pk_mul_f32 v[124:125], v[124:125], v[230:231]
	v_cvt_pk_bf16_f32 v4, v121, v119
	ds_write_b16 v158, v2
	ds_write_b16_d16_hi v161, v4
	v_cvt_pk_bf16_f32 v2, v134, v128
	v_cvt_pk_bf16_f32 v4, v122, v124
	ds_write_b16 v162, v2
	ds_write_b16_d16_hi v165, v4
	v_cvt_pk_bf16_f32 v2, v135, v129
	v_cvt_pk_bf16_f32 v4, v123, v125
	ds_write_b16 v166, v2
	ds_write_b16_d16_hi v169, v4
	v_cvt_pk_bf16_f32 v118, v126, v127
	v_cvt_pk_bf16_f32 v119, v128, v129
	v_cvt_pk_bf16_f32 v120, v120, v121
	v_cvt_pk_bf16_f32 v121, v122, v123
	v_add_u32_e32 v2, v149, v170
	ds_write_b128 v2, v[118:121]
	s_and_saveexec_b64 s[18:19], s[10:11]
	s_cbranch_execz .LBB0_554
	s_waitcnt lgkmcnt(8)
	v_pk_add_f32 v[118:119], v[138:139], v[136:137]
	s_nop 0
	v_add_f32_e32 v2, v118, v119
	v_exp_f32_e32 v2, v2
	ds_write_b32 v171, v2 offset:20992
.LBB0_554:
	s_or_b64 exec, exec, s[18:19]
	v_mov_b32_e32 v2, v133
	v_pk_add_f32 v[82:83], v[2:3], v[82:83] op_sel_hi:[0,1]
	v_exp_f32_e32 v82, v82
	v_exp_f32_e32 v83, v83
	v_pk_add_f32 v[84:85], v[2:3], v[84:85] op_sel_hi:[0,1]
	v_exp_f32_e32 v84, v84
	v_exp_f32_e32 v85, v85
	v_pk_add_f32 v[82:83], v[82:83], 1.0 op_sel_hi:[1,0]
	v_or_b32_e32 v4, 64, v202
	v_rcp_f32_e32 v82, v82
	v_rcp_f32_e32 v83, v83
	v_pk_add_f32 v[84:85], v[84:85], 1.0 op_sel_hi:[1,0]
	v_or_b32_e32 v86, 0x80, v202
	v_rcp_f32_e32 v84, v84
	v_rcp_f32_e32 v85, v85
	v_pk_mul_f32 v[122:123], v[82:83], s[70:71] op_sel_hi:[1,0]
	v_or_b32_e32 v88, 0xc0, v202
	v_pk_fma_f32 v[124:125], v[82:83], s[70:71], v[122:123] op_sel:[0,0,1] op_sel_hi:[1,0,0]
	v_mul_f32_e32 v2, 0xbf60028a, v85
	v_pk_fma_f32 v[126:127], v[84:85], s[70:71], v[124:125] op_sel_hi:[1,0,1]
	v_mov_b32_e32 v123, v124
	v_pk_add_f32 v[128:129], v[2:3], v[126:127] op_sel_hi:[0,1]
	ds_bpermute_b32 v82, v202, v128
	ds_bpermute_b32 v84, v4, v128
	ds_bpermute_b32 v83, v86, v128
	v_mov_b32_e32 v127, v128
	v_mov_b32_e32 v104, v105
	s_waitcnt lgkmcnt(2)
	v_cndmask_b32_e64 v4, v82, 0, s[10:11]
	s_waitcnt lgkmcnt(1)
	v_cndmask_b32_e64 v86, 0, v84, s[12:13]
	v_add_f32_e32 v4, v4, v86
	s_waitcnt lgkmcnt(0)
	v_cndmask_b32_e64 v86, 0, v83, s[14:15]
	v_add_f32_e32 v4, v4, v86
	v_pk_add_f32 v[124:125], v[122:123], v[4:5] op_sel_hi:[1,0]
	v_pk_add_f32 v[126:127], v[126:127], v[4:5] op_sel_hi:[1,0]
	v_sub_f32_e32 v4, v124, v122
	v_exp_f32_e32 v122, v4
	v_mov_b32_e32 v4, v117
	v_pk_add_f32 v[80:81], v[4:5], v[80:81] op_sel_hi:[0,1]
	v_pk_add_f32 v[78:79], v[4:5], v[78:79] op_sel_hi:[0,1]
	v_exp_f32_e32 v80, v80
	v_exp_f32_e32 v81, v81
	v_exp_f32_e32 v78, v78
	v_exp_f32_e32 v79, v79
	v_mov_b32_e32 v86, v95
	v_mov_b32_e32 v105, v112
	v_mov_b32_e32 v118, v113
	v_mov_b32_e32 v119, v114
	ds_bpermute_b32 v85, v88, v128
	v_pk_add_f32 v[80:81], v[80:81], 1.0 op_sel_hi:[1,0]
	v_mov_b32_e32 v4, v91
	v_pk_mul_f32 v[90:91], v[112:113], v[86:87] op_sel_hi:[1,0]
	v_mov_b32_e32 v88, v93
	v_pk_mul_f32 v[92:93], v[114:115], v[86:87] op_sel_hi:[1,0]
	v_mov_b32_e32 v86, v103
	v_mov_b32_e32 v106, v107
	v_mov_b32_e32 v107, v108
	v_mov_b32_e32 v98, v115
	v_pk_add_f32 v[78:79], v[78:79], 1.0 op_sel_hi:[1,0]
	v_rcp_f32_e32 v80, v80
	v_rcp_f32_e32 v81, v81
	v_pk_fma_f32 v[90:91], v[104:105], v[4:5], v[90:91] op_sel_hi:[1,0,1]
	v_pk_fma_f32 v[92:93], v[118:119], v[4:5], v[92:93] op_sel_hi:[1,0,1]
	v_mov_b32_e32 v4, v87
	v_pk_mul_f32 v[94:95], v[108:109], v[86:87] op_sel_hi:[1,0]
	v_mov_b32_e32 v120, v109
	v_mov_b32_e32 v121, v110
	v_exp_f32_e32 v128, v124
	v_rcp_f32_e32 v78, v78
	v_rcp_f32_e32 v79, v79
	v_pk_fma_f32 v[90:91], v[118:119], v[88:89], v[90:91] op_sel_hi:[1,0,1]
	v_pk_fma_f32 v[92:93], v[98:99], v[88:89], v[92:93] op_sel_hi:[1,0,1]
	v_pk_fma_f32 v[94:95], v[106:107], v[4:5], v[94:95] op_sel_hi:[1,0,1]
	v_mov_b32_e32 v88, v101
	v_pk_mul_f32 v[86:87], v[110:111], v[86:87] op_sel_hi:[1,0]
	v_mov_b32_e32 v2, v111
	v_pk_fma_f32 v[94:95], v[120:121], v[88:89], v[94:95] op_sel_hi:[1,0,1]
	v_pk_fma_f32 v[86:87], v[120:121], v[4:5], v[86:87] op_sel_hi:[1,0,1]
	v_mov_b32_e32 v4, v97
	v_exp_f32_e32 v129, v125
	v_exp_f32_e32 v130, v126
	v_exp_f32_e64 v132, -v124
	v_exp_f32_e64 v133, -v125
	v_pk_fma_f32 v[2:3], v[2:3], v[88:89], v[86:87] op_sel_hi:[1,0,1]
	v_pk_mul_f32 v[86:87], v[4:5], v[94:95] op_sel_hi:[0,1]
	v_pk_mul_f32 v[74:75], v[74:75], v[86:87]
	v_pk_mul_f32 v[86:87], v[4:5], v[2:3] op_sel_hi:[0,1]
	v_mov_b32_e32 v4, v89
	v_pk_add_f32 v[88:89], v[80:81], -1.0 op_sel_hi:[1,0]
	v_exp_f32_e32 v131, v127
	v_exp_f32_e64 v126, -v126
	v_exp_f32_e64 v127, -v127
	v_mov_b32_e32 v123, v128
	v_pk_mul_f32 v[76:77], v[76:77], v[86:87]
	v_pk_add_f32 v[86:87], v[78:79], -1.0 op_sel_hi:[1,0]
	v_pk_mul_f32 v[88:89], v[4:5], v[88:89] op_sel_hi:[0,1]
	v_pk_mul_f32 v[86:87], v[4:5], v[86:87] op_sel_hi:[0,1]
	v_pk_fma_f32 v[2:3], v[2:3], v[88:89], v[2:3]
	v_pk_mul_f32 v[88:89], v[74:75], v[122:123] neg_lo:[0,1] neg_hi:[0,1]
	v_pk_mul_f32 v[74:75], v[74:75], v[78:79]
	v_mov_b32_e32 v124, v129
	v_mov_b32_e32 v125, v130
	v_pk_fma_f32 v[86:87], v[94:95], v[86:87], v[94:95]
	v_pk_mul_f32 v[74:75], v[74:75], v[132:133]
	v_pk_mul_f32 v[94:95], v[76:77], v[124:125] neg_lo:[0,1] neg_hi:[0,1]
	v_pk_mul_f32 v[76:77], v[76:77], v[80:81]
	v_pk_mul_f32 v[78:79], v[86:87], v[132:133]
	v_pk_mul_f32 v[80:81], v[90:91], v[128:129]
	v_cvt_pk_bf16_f32 v4, v88, v74
	v_pk_mul_f32 v[76:77], v[76:77], v[126:127]
	v_cvt_pk_bf16_f32 v80, v78, v80
	ds_write_b16 v172, v4
	ds_write_b16_d16_hi v175, v80
	v_cvt_pk_bf16_f32 v4, v89, v75
	v_pk_mul_f32 v[2:3], v[2:3], v[126:127]
	v_pk_mul_f32 v[86:87], v[92:93], v[130:131]
	v_cvt_pk_bf16_f32 v80, v79, v81
	ds_write_b16 v176, v4
	ds_write_b16_d16_hi v179, v80
	v_cvt_pk_bf16_f32 v4, v94, v76
	v_cvt_pk_bf16_f32 v80, v2, v86
	ds_write_b16 v180, v4
	ds_write_b16_d16_hi v183, v80
	v_cvt_pk_bf16_f32 v4, v95, v77
	v_cvt_pk_bf16_f32 v74, v74, v75
	v_cvt_pk_bf16_f32 v75, v76, v77
	v_cvt_pk_bf16_f32 v76, v78, v79
	v_cvt_pk_bf16_f32 v77, v2, v3
	v_cvt_pk_bf16_f32 v80, v3, v87
	ds_write_b16 v184, v4
	ds_write_b16_d16_hi v187, v80
	ds_write_b128 v194, v[74:77]
	s_and_saveexec_b64 s[18:19], s[10:11]
	s_cbranch_execz .LBB0_556
	s_waitcnt lgkmcnt(8)
	v_pk_add_f32 v[2:3], v[84:85], v[82:83]
	s_nop 0
	v_add_f32_e32 v2, v2, v3
	v_exp_f32_e32 v2, v2
	ds_write_b32 v171, v2 offset:21056

.LBB0_568:
	s_or_b64 exec, exec, s[22:23]
	v_mov_b32_e32 v3, v0
	s_mov_b64 s[22:23], -1
	v_and_b32_e32 v88, 15, v3
	s_waitcnt vmcnt(5)
	v_lshrrev_b32_e32 v66, 4, v3
	v_and_b32_e32 v67, 7, v3
	v_bfe_u32 v2, v3, 4, 2
	v_or_b32_e32 v4, s82, v88
	v_bitop3_b32 v66, v66, v67, 3 bitop3:0x6c
	v_lshlrev_b32_e32 v83, 7, v4
	v_lshlrev_b32_e32 v84, 4, v66
	v_bitop3_b32 v66, v2, v67, 4 bitop3:0x36
	v_lshlrev_b32_e32 v82, 4, v66
	v_add_u32_e32 v70, s89, v83
	v_add_u32_e32 v66, v70, v84
	v_add_u32_e32 v70, v70, v82
	ds_read_b128 v[66:69], v66
	ds_read_b128 v[70:73], v70
	ds_read_b64_tr_b16 v[74:75], v241
	ds_read_b64_tr_b16 v[76:77], v241 offset:1024
	ds_read_b64_tr_b16 v[78:79], v241 offset:2048
	ds_read_b64_tr_b16 v[80:81], v241 offset:3072
	v_lshlrev_b32_e32 v92, 2, v2
	s_and_b64 vcc, exec, s[4:5]
	v_lshlrev_b32_e32 v86, 5, v4
	v_lshlrev_b32_e32 v87, 3, v2
	v_cmp_lt_u32_e64 s[18:19], v92, v88
	v_or_b32_e32 v91, 1, v92
	v_or_b32_e32 v90, 2, v92
	v_or_b32_e32 v89, 3, v92
	s_cbranch_vccz .LBB0_576
	v_add_u32_e32 v85, s92, v83
	v_add_u32_e32 v93, v85, v84
	v_add_u32_e32 v85, v85, v82
	ds_read_b128 v[98:101], v85
	ds_read_b64_tr_b16 v[106:107], v241 offset:8
	ds_read_b64_tr_b16 v[108:109], v241 offset:1032
	ds_read_b128 v[94:97], v93
	ds_read_b64_tr_b16 v[82:83], v241 offset:2056
	ds_read_b64_tr_b16 v[84:85], v241 offset:3080
	s_waitcnt lgkmcnt(2)
	v_mfma_f32_16x16x32_bf16 v[102:105], v[74:77], v[94:97], 0
	v_cmp_gt_u32_e64 s[24:25], v90, v88
	v_mov_b32_e32 v118, s67
	v_mov_b32_e32 v120, s67
	v_mfma_f32_16x16x32_bf16 v[114:117], v[106:109], v[94:97], 0
	v_cmp_gt_u32_e32 vcc, v92, v88
	v_cmp_lt_u32_e64 s[22:23], v90, v88
	v_lshlrev_b32_e32 v4, 6, v4
	v_mfma_f32_16x16x32_bf16 v[110:113], v[106:109], v[66:69], 0
	v_lshlrev_b32_e32 v122, 16, v94
	v_and_b32_e32 v123, 0xffff0000, v94
	v_and_b32_e32 v3, 3, v3
	v_mfma_f32_16x16x32_bf16 v[102:105], v[78:81], v[98:101], v[102:105]
	s_waitcnt lgkmcnt(0)
	v_mfma_f32_16x16x32_bf16 v[114:117], v[82:85], v[98:101], v[114:117]
	v_mfma_f32_16x16x32_bf16 v[110:113], v[82:85], v[70:73], v[110:113]
	s_nop 4
	v_cndmask_b32_e64 v104, v104, 0, s[24:25]
	s_nop 0
	v_cndmask_b32_e64 v116, v116, 0, s[24:25]
	v_cmp_lt_u32_e64 s[24:25], v89, v88
	v_cndmask_b32_e32 v93, v114, v120, vcc
	v_cndmask_b32_e32 v118, v102, v118, vcc
	v_cmp_lt_u32_e32 vcc, v91, v88
	s_or_b64 s[22:23], s[24:25], s[22:23]
	s_or_b64 vcc, s[22:23], vcc
	v_cndmask_b32_e64 v93, v93, v114, s[18:19]
	v_cndmask_b32_e64 v114, 0, v115, s[18:19]
	v_cndmask_b32_e64 v115, v118, v102, s[18:19]
	v_cndmask_b32_e32 v102, 0, v111, vcc
	s_or_b64 vcc, vcc, s[18:19]
	v_cndmask_b32_e64 v118, 0, v103, s[18:19]
	v_cndmask_b32_e64 v103, 0, v113, s[24:25]
	v_cndmask_b32_e64 v112, 0, v112, s[22:23]
	v_cndmask_b32_e32 v110, 0, v110, vcc
	v_cmp_gt_u32_e32 vcc, v89, v88
	v_cvt_pk_bf16_f32 v102, v110, v102
	v_cvt_pk_bf16_f32 v103, v112, v103
	v_cndmask_b32_e64 v105, v105, 0, vcc
	v_add3_u32 v110, s72, v86, v87
	v_cndmask_b32_e64 v111, v117, 0, vcc
	ds_write_b64 v110, v[102:103]
	v_cvt_pk_bf16_f32 v103, v104, v105
	v_cvt_pk_bf16_f32 v104, v93, v114
	v_lshlrev_b32_e32 v93, 4, v2
	v_cvt_pk_bf16_f32 v102, v115, v118
	v_cvt_pk_bf16_f32 v105, v116, v111
	v_add3_u32 v4, s71, v4, v93
	ds_write_b128 v4, v[102:105]
	v_lshl_add_u32 v4, v2, 5, 0
	ds_read_b128 v[102:105], v4 offset:22016
	ds_read_b128 v[110:113], v4 offset:22032
	ds_read_b128 v[114:117], v4 offset:22144
	ds_read_b128 v[118:121], v4 offset:22160
	v_cmp_lt_i32_e32 vcc, 0, v3
	s_waitcnt lgkmcnt(3)
	v_pk_mul_f32 v[102:103], v[102:103], v[122:123]
	s_nop 0
	v_cvt_pk_bf16_f32 v94, v102, v103
	v_lshlrev_b32_e32 v102, 16, v98
	v_and_b32_e32 v103, 0xffff0000, v98
	s_waitcnt lgkmcnt(1)
	v_pk_mul_f32 v[102:103], v[114:115], v[102:103]
	s_nop 0
	v_cvt_pk_bf16_f32 v98, v102, v103
	v_lshlrev_b32_e32 v102, 16, v95
	v_and_b32_e32 v103, 0xffff0000, v95
	v_pk_mul_f32 v[102:103], v[104:105], v[102:103]
	s_nop 0
	v_cvt_pk_bf16_f32 v95, v102, v103
	v_lshlrev_b32_e32 v102, 16, v99
	v_and_b32_e32 v103, 0xffff0000, v99
	v_pk_mul_f32 v[102:103], v[116:117], v[102:103]
	s_nop 0
	v_cvt_pk_bf16_f32 v99, v102, v103
	v_lshlrev_b32_e32 v102, 16, v96
	v_and_b32_e32 v103, 0xffff0000, v96
	v_pk_mul_f32 v[102:103], v[110:111], v[102:103]
	s_nop 0
	v_cvt_pk_bf16_f32 v96, v102, v103
	v_lshlrev_b32_e32 v102, 16, v100
	v_and_b32_e32 v103, 0xffff0000, v100
	s_waitcnt lgkmcnt(0)
	v_pk_mul_f32 v[102:103], v[118:119], v[102:103]
	s_nop 0
	v_cvt_pk_bf16_f32 v100, v102, v103
	v_lshlrev_b32_e32 v102, 16, v97
	v_and_b32_e32 v103, 0xffff0000, v97
	v_pk_mul_f32 v[102:103], v[112:113], v[102:103]
	s_nop 0
	v_cvt_pk_bf16_f32 v97, v102, v103
	v_lshlrev_b32_e32 v102, 16, v101
	v_and_b32_e32 v103, 0xffff0000, v101
	v_mfma_f32_16x16x32_bf16 v[94:97], v[106:109], v[94:97], 0
	v_mul_f32_e64 v102, v120, v102
	v_mul_f32_e64 v103, v121, v103
	v_cvt_pk_bf16_f32 v101, v102, v103
	s_nop 1
	v_mfma_f32_16x16x32_bf16 v[82:85], v[82:85], v[98:101], v[94:97]
	s_and_saveexec_b64 s[18:19], vcc
	s_xor_b64 s[18:19], exec, s[18:19]
	s_cbranch_execz .LBB0_573
	v_cmp_ne_u32_e32 vcc, 1, v3
	s_nop 3
	v_mov_b32_e32 v82, v83
	s_and_saveexec_b64 s[22:23], vcc
	s_xor_b64 s[22:23], exec, s[22:23]
	v_cmp_eq_u32_e32 vcc, 2, v3
	s_nop 1
	v_cndmask_b32_e32 v82, v85, v84, vcc
	s_andn2_saveexec_b64 s[22:23], s[22:23]
	s_or_b64 exec, exec, s[22:23]

.LBB0_576:
	s_and_b64 vcc, exec, s[22:23]
	s_cbranch_vccz .LBB0_578
	s_waitcnt lgkmcnt(2)
	v_mfma_f32_16x16x32_bf16 v[82:85], v[66:69], v[74:77], 0
	v_cmp_lt_u32_e64 s[22:23], v88, v90
	v_cmp_lt_u32_e64 s[24:25], v88, v89
	v_cmp_lt_u32_e32 vcc, v88, v92
	s_waitcnt lgkmcnt(0)
	v_mfma_f32_16x16x32_bf16 v[82:85], v[70:73], v[78:81], v[82:85]
	v_mov_b32_e32 v2, s67
	v_cmp_lt_u32_e64 s[18:19], v91, v88
	v_mfma_f32_16x16x32_bf16 v[66:69], v[74:77], v[66:69], 0
	v_mfma_f32_16x16x32_bf16 v[66:69], v[78:81], v[70:73], v[66:69]
	s_nop 3
	v_cndmask_b32_e64 v4, 0, v84, s[22:23]
	v_cmp_lt_u32_e64 s[22:23], v90, v88
	v_cndmask_b32_e64 v70, 0, v85, s[24:25]
	v_cmp_lt_u32_e64 s[24:25], v89, v88
	s_or_b64 s[22:23], s[24:25], s[22:23]
	v_cndmask_b32_e32 v2, v2, v82, vcc
	v_cmp_lt_u32_e32 vcc, v92, v88
	s_or_b64 s[18:19], s[22:23], s[18:19]
	v_cndmask_b32_e64 v76, 0, v68, s[22:23]
	v_cndmask_b32_e64 v3, v83, 0, vcc
	s_or_b64 vcc, s[18:19], vcc
	v_cndmask_b32_e64 v75, 0, v67, s[18:19]
	v_cndmask_b32_e32 v74, 0, v66, vcc
	v_cndmask_b32_e64 v77, 0, v69, s[24:25]
	v_cvt_pk_bf16_f32 v2, v2, v3
	v_cvt_pk_bf16_f32 v3, v4, v70
	v_mov_b32_e32 v4, v5
	v_cvt_pk_bf16_f32 v66, v74, v75
	v_cvt_pk_bf16_f32 v67, v76, v77
	v_mov_b32_e32 v68, v5
	v_mov_b32_e32 v69, v5
	v_cmp_eq_u32_e32 vcc, v92, v88
	v_add_f32_e32 v78, 1.0, v74
	v_mfma_f32_16x16x32_bf16 v[70:73], v[66:69], v[2:5], 0
	v_cndmask_b32_e32 v74, v74, v78, vcc
	v_cmp_eq_u32_e32 vcc, v91, v88
	v_add_f32_e32 v78, 1.0, v75
	v_mfma_f32_16x16x32_bf16 v[66:69], v[2:5], v[66:69], 0
	s_nop 3
	v_cvt_pk_bf16_f32 v2, v70, v71
	v_cvt_pk_bf16_f32 v3, v72, v73
	v_cndmask_b32_e32 v75, v75, v78, vcc
	v_cmp_eq_u32_e32 vcc, v90, v88
	v_add_f32_e32 v78, 1.0, v76
	v_cvt_pk_bf16_f32 v66, v66, v67
	v_cvt_pk_bf16_f32 v67, v68, v69
	v_mov_b32_e32 v68, v5
	v_mov_b32_e32 v69, v5
	v_cndmask_b32_e32 v76, v76, v78, vcc
	v_cmp_eq_u32_e32 vcc, v89, v88
	v_mfma_f32_16x16x32_bf16 v[70:73], v[66:69], v[2:5], 0
	v_add_f32_e32 v78, 1.0, v77
	v_cndmask_b32_e32 v77, v77, v78, vcc
	v_cvt_pk_bf16_f32 v78, v74, v75
	v_mfma_f32_16x16x32_bf16 v[66:69], v[2:5], v[66:69], 0
	v_cvt_pk_bf16_f32 v79, v76, v77
	v_mov_b32_e32 v80, v5
	v_mov_b32_e32 v81, v5
	s_nop 0
	v_cvt_pk_bf16_f32 v70, v70, v71
	v_cvt_pk_bf16_f32 v71, v72, v73
	s_nop 1
	v_cvt_pk_bf16_f32 v66, v66, v67
	v_cvt_pk_bf16_f32 v67, v68, v69
	v_mov_b32_e32 v68, v5
	v_mov_b32_e32 v69, v5
	v_mov_b32_e32 v72, v5
	v_mov_b32_e32 v73, v5
	v_mfma_f32_16x16x32_bf16 v[74:77], v[2:5], v[78:81], v[74:77]
	s_nop 0
	v_mfma_f32_16x16x32_bf16 v[66:69], v[66:69], v[70:73], 0
	s_nop 5
	v_cvt_pk_bf16_f32 v2, v74, v75
	v_cvt_pk_bf16_f32 v3, v76, v77
	s_nop 1
	v_mfma_f32_16x16x32_bf16 v[70:73], v[70:73], v[2:5], v[74:77]
	v_cvt_pk_bf16_f32 v2, v66, v67
	v_cvt_pk_bf16_f32 v3, v68, v69
	v_mov_b32_e32 v68, v5
	v_mov_b32_e32 v69, v5
	s_nop 3
	v_cvt_pk_bf16_f32 v66, v70, v71
	v_cvt_pk_bf16_f32 v67, v72, v73
	s_nop 1
	v_mfma_f32_16x16x32_bf16 v[66:69], v[2:5], v[66:69], v[70:73]
	v_add3_u32 v4, s33, v86, v87
	s_nop 6
	v_cvt_pk_bf16_f32 v2, v66, v67
	v_cvt_pk_bf16_f32 v3, v68, v69
	ds_write_b64 v4, v[2:3]
